# GEMM phase prologue de-serialised: all 14 first-tile LDS-DMA loads issued before the first counted wait (vmcnt 2 -> 8 behind the second batch)
# speedup vs baseline: 1.5396x; 1.5396x over previous
.LBB0_331:
	s_lshl_b32 s1, s7, 5
	s_and_b32 s1, s1, 0x60
	s_lshl_b32 s86, s2, 6
	s_lshl_b32 s0, s2, 13
	s_lshl_b32 s7, s1, 7
	s_add_u32 s82, s16, 0x20100000
	s_addc_u32 s83, s17, 0
	s_add_i32 m0, s67, 0x18000
	v_lshl_add_u64 v[2:3], v[2:3], 0, s[94:95]
	global_load_lds_dwordx4 v[2:3], off
	v_lshl_add_u64 v[2:3], v[4:5], 0, s[94:95]
	s_add_i32 m0, s67, 0x1a000
	s_add_i32 s87, s67, 0x8000
	global_load_lds_dwordx4 v[2:3], off
	v_lshl_add_u64 v[2:3], v[10:11], 0, s[94:95]
	s_mov_b32 m0, s87
	s_add_i32 s2, s67, 0xa000
	global_load_lds_dwordx4 v[2:3], off
	v_lshl_add_u64 v[2:3], v[12:13], 0, s[94:95]
	s_mov_b32 m0, s2
	v_and_b32_e32 v188, 15, v222
	global_load_lds_dwordx4 v[2:3], off
	s_add_i32 m0, s67, 0x1c000
	v_lshl_add_u64 v[2:3], v[6:7], 0, s[94:95]
	global_load_lds_dwordx4 v[2:3], off
	v_lshl_add_u64 v[2:3], v[8:9], 0, s[94:95]
	s_add_i32 m0, s67, 0x1e000
	v_lshlrev_b32_e32 v4, 2, v222
	global_load_lds_dwordx4 v[2:3], off
	s_waitcnt vmcnt(8)
	s_barrier
	v_bfe_u32 v2, v222, 4, 2
	v_lshlrev_b32_e32 v3, 4, v2
	s_cmpk_lt_u32 s9, 0x100
	v_lshl_or_b32 v3, v188, 6, v3
	v_and_b32_e32 v4, 32, v4
	s_cselect_b64 s[84:85], -1, 0
	s_lshl_b32 s35, s35, 3
	v_bitop3_b32 v5, v3, s0, v4 bitop3:0xde
	v_bitop3_b32 v223, s7, v3, v4 bitop3:0xf6
	v_cvt_f32_u32_e32 v3, s35
	v_cmp_gt_u32_e64 s[14:15], 2, v188
	s_lshr_b32 s73, s3, 6
	s_lshr_b32 s3, s3, 10
	v_writelane_b32 v245, s14, 62
	s_and_b32 s34, s34, 4
	s_lshr_b32 s0, s8, 3
	v_writelane_b32 v245, s15, 63
	s_add_u32 s14, s92, 0x5800
	v_rcp_iflag_f32_e32 v3, v3
	s_addc_u32 s15, s93, 0
	v_writelane_b32 v244, s14, 30
	v_add_u32_e32 v0, v18, v0
	v_mul_f32_e32 v3, 0x4f7ffffe, v3
	v_writelane_b32 v244, s15, 31
	s_add_u32 s14, s92, 0xb000
	s_addc_u32 s15, s93, 0
	v_writelane_b32 v244, s14, 32
	v_cvt_u32_f32_e32 v3, v3
	v_writelane_b32 v245, s0, 60
	v_writelane_b32 v244, s15, 33
	s_add_u32 s14, s16, 0x20d60000
	s_addc_u32 s15, s17, 0
	s_add_u32 s74, s16, 0x219c0000
	s_addc_u32 s75, s17, 0
	v_lshl_or_b32 v224, v2, 3, s1
	v_lshl_or_b32 v225, v2, 2, s1
	s_sub_i32 s0, 0, s35
	v_readfirstlane_b32 s1, v3
	v_add_lshl_u32 v0, v0, v17, 1
	s_waitcnt vmcnt(6)
	s_mul_i32 s0, s0, s1
	v_lshl_add_u64 v[192:193], s[90:91], 0, v[0:1]
	v_add_u32_e32 v0, v16, v14
	v_writelane_b32 v244, s14, 34
	s_mul_hi_u32 s0, s1, s0
	v_add_lshl_u32 v0, v0, v15, 1
	v_cmp_lt_u32_e64 s[42:43], 1, v188
	v_cmp_lt_u32_e64 s[44:45], 13, v188
	v_add_u32_e32 v190, -14, v188
	s_mov_b32 s7, s89
	s_mov_b32 s9, s89
	v_writelane_b32 v244, s15, 35
	s_mov_b32 s80, 0
	s_add_i32 s0, s1, s0
	v_lshl_add_u64 v[194:195], s[90:91], 0, v[0:1]
	v_add_u32_e32 v226, 0, v5
	s_barrier
	v_writelane_b32 v244, s0, 36
	s_branch .LBB0_334
